# seam prefetch (weight tiles only) extended to the P8 seam and the seam in front of the next layer's P1
# speedup vs baseline: 1.0033x; 1.0033x over previous
.LBB0_704:
	v_readlane_b32 s0, v254, 38
	s_or_b32 s2, s0, 7
	v_readlane_b32 s0, v252, 6
	v_readlane_b32 s1, v252, 7
	s_cmp_lt_i32 s2, s1
	s_cselect_b64 s[0:1], -1, 0
	s_and_b64 s[4:5], s[10:11], s[0:1]
	s_andn2_b64 vcc, exec, s[4:5]
	s_cbranch_vccnz .LBB0_754
	s_waitcnt vmcnt(0)
	s_barrier
	s_mov_b64 s[10:11], exec
	v_readlane_b32 s4, v252, 4
	v_readlane_b32 s5, v252, 5
	s_and_b64 s[4:5], s[10:11], s[4:5]
	s_mov_b64 exec, s[4:5]
	s_cbranch_execz .Lseam_pf8
	s_branch .Lseam_lead8
.Lseam_pf8:
	s_mov_b64 exec, s[10:11]
	v_readlane_b32 s78, v254, 20
	v_mov_b32_e32 v2, s78
	ds_read_b64 v[2:3], v2
	v_mbcnt_lo_u32_b32 v4, -1, 0
	v_mbcnt_hi_u32_b32 v4, -1, v4
	v_readlane_b32 s79, v252, 2
	v_readlane_b32 s82, v252, 8
	v_readlane_b32 s83, v254, 36
	s_waitcnt lgkmcnt(0)
	v_readfirstlane_b32 s80, v2
	v_readfirstlane_b32 s81, v3
	s_and_b32 s84, s79, 1
	s_lshl_b32 s84, s84, 2
	s_lshr_b32 s85, s79, 6
	s_add_i32 s84, s84, s85
	s_lshr_b32 s82, s82, 6
	s_add_i32 s82, s82, -1
	s_lshl_b32 s85, s82, 8
	s_add_i32 s85, s85, 0x21000
	s_mov_b32 m0, s85
	s_and_b32 s84, s79, 7
	s_mul_i32 s84, s84, 176
	s_lshr_b32 s85, s79, 3
	s_add_i32 s84, s84, s85
	s_cmp_ge_u32 s84, 352
	s_cselect_b32 s85, 352, 0
	s_sub_i32 s84, s84, s85
	s_cmp_ge_u32 s84, 352
	s_cselect_b32 s85, 352, 0
	s_sub_i32 s84, s84, s85
	s_cmp_ge_u32 s84, 352
	s_cselect_b32 s85, 352, 0
	s_sub_i32 s84, s84, s85
	s_lshr_b32 s84, s84, 3
	s_mul_i32 s86, s83, 0x2c00000
	s_mul_i32 s87, s84, 0x100000
	s_add_u32 s86, s86, s87
	s_add_u32 s86, s86, 0x18500000
	s_add_u32 s86, s80, s86
	s_addc_u32 s87, s81, 0
	v_lshrrev_b32_e32 v5, 1, v4
	v_lshl_add_u32 v5, s82, 5, v5
	v_mul_u32_u24_e32 v5, 0x1000, v5
	v_and_b32_e32 v6, 1, v4
	v_lshl_add_u32 v5, v6, 7, v5
	global_load_lds_dword v5, s[86:87]
	s_branch .LBB0_753

.LBB0_1097:
	s_waitcnt vmcnt(0)
	s_barrier
	s_mov_b64 s[0:1], exec
	v_readlane_b32 s4, v252, 4
	v_readlane_b32 s5, v252, 5
	s_and_b64 s[4:5], s[0:1], s[4:5]
	s_mov_b64 exec, s[4:5]
	s_cbranch_execnz .LBB0_1098
	s_mov_b64 exec, s[0:1]
	v_readlane_b32 s78, v254, 20
	v_mov_b32_e32 v2, s78
	ds_read_b64 v[2:3], v2
	v_mbcnt_lo_u32_b32 v4, -1, 0
	v_mbcnt_hi_u32_b32 v4, -1, v4
	v_readlane_b32 s79, v252, 2
	v_readlane_b32 s82, v252, 8
	v_readlane_b32 s83, v254, 36
	s_waitcnt lgkmcnt(0)
	v_readfirstlane_b32 s80, v2
	v_readfirstlane_b32 s81, v3
	s_and_b32 s84, s79, 1
	s_lshl_b32 s84, s84, 2
	s_lshr_b32 s85, s79, 6
	s_add_i32 s84, s84, s85
	s_lshr_b32 s82, s82, 6
	s_add_i32 s82, s82, -1
	s_lshl_b32 s85, s82, 8
	s_add_i32 s85, s85, 0x21000
	s_mov_b32 m0, s85
	s_add_i32 s83, s83, 1
	s_and_b32 s84, s79, 7
	s_mul_i32 s84, s84, 308
	s_lshr_b32 s85, s79, 3
	s_add_i32 s84, s84, s85
	s_cmp_ge_u32 s84, 616
	s_cselect_b32 s85, 616, 0
	s_sub_i32 s84, s84, s85
	s_cmp_ge_u32 s84, 616
	s_cselect_b32 s85, 616, 0
	s_sub_i32 s84, s84, s85
	s_cmp_ge_u32 s84, 616
	s_cselect_b32 s85, 616, 0
	s_sub_i32 s84, s84, s85
	s_lshr_b32 s84, s84, 3
	s_cmp_lt_u32 s84, 8
	s_cselect_b32 s85, 68, 0
	s_sub_i32 s86, s84, 68
	s_cmp_lt_u32 s86, 8
	s_cselect_b32 s86, -68, 0
	s_add_i32 s84, s84, s85
	s_add_i32 s84, s84, s86
	s_mul_i32 s86, s83, 0x4d00000
	s_mul_i32 s87, s84, 0x100000
	s_add_u32 s86, s86, s87
	s_add_u32 s86, s86, 0x100000
	s_add_u32 s86, s80, s86
	s_addc_u32 s87, s81, 0
	v_lshrrev_b32_e32 v5, 1, v4
	v_lshl_add_u32 v5, s82, 5, v5
	v_mul_u32_u24_e32 v5, 0x1000, v5
	v_and_b32_e32 v6, 1, v4
	v_lshl_add_u32 v5, v6, 7, v5
	global_load_lds_dword v5, s[86:87]
	s_mov_b64 exec, 0
	s_getpc_b64 s[98:99]
